# GEMM4 final-output stores: plain (write-back) instead of nontemporal, so the store burst is absorbed by L2 and does not block the next tile's loads behind it in vmcnt order
# speedup vs baseline: 1.0180x; 1.0180x over previous
.LBB0_913:
	s_or_b64 exec, exec, s[38:39]
	v_lshlrev_b64 v[64:65], 2, v[174:175]
	s_waitcnt vmcnt(0) lgkmcnt(0)
	s_barrier
	v_lshl_add_u64 v[66:67], s[12:13], 0, v[64:65]
	global_load_dwordx4 v[4:7], v[66:67], off
	global_load_dwordx4 v[0:3], v[66:67], off offset:16
	s_add_i32 s1, 0, 0x21000
	v_lshlrev_b64 v[78:79], 13, v[170:171]
	v_lshl_add_u32 v199, v194, 2, s1
	v_lshl_add_u64 v[86:87], s[14:15], 0, v[78:79]
	v_lshlrev_b64 v[76:77], 13, v[172:173]
	v_lshlrev_b64 v[82:83], 13, v[168:169]
	v_lshlrev_b64 v[80:81], 13, v[166:167]
	ds_read2_b32 v[168:169], v199 offset1:16
	v_lshl_add_u64 v[172:173], v[86:87], 0, v[64:65]
	ds_read2_b32 v[166:167], v199 offset0:16 offset1:32
	ds_read2_b32 v[86:87], v199 offset0:32 offset1:48
	v_add_u32_e32 v195, 0x80, v194
	v_lshl_add_u64 v[84:85], s[14:15], 0, v[76:77]
	v_lshl_add_u32 v197, v195, 2, s1
	v_lshl_add_u64 v[170:171], v[84:85], 0, v[64:65]
	ds_read_b32 v196, v199
	ds_read_b32 v84, v199 offset:704
	ds_read_b32 v198, v197
	ds_read_b32 v200, v197
	v_add_u32_e32 v194, s0, v195
	v_ashrrev_i32_e32 v195, 31, v194
	v_lshlrev_b64 v[194:195], 13, v[194:195]
	s_waitcnt lgkmcnt(3)
	v_pk_mul_f32 v[126:127], v[126:127], v[196:197] op_sel_hi:[1,0]
	v_pk_mul_f32 v[124:125], v[124:125], v[196:197] op_sel_hi:[1,0]
	v_pk_mul_f32 v[122:123], v[122:123], v[196:197] op_sel_hi:[1,0]
	v_pk_mul_f32 v[120:121], v[120:121], v[196:197] op_sel_hi:[1,0]
	v_mov_b32_e32 v196, v169
	v_mov_b32_e32 v204, v167
	v_mov_b32_e32 v206, v87
	v_lshl_add_u64 v[174:175], s[14:15], 0, v[82:83]
	v_lshl_add_u64 v[182:183], s[14:15], 0, v[80:81]
	v_lshl_add_u64 v[202:203], s[14:15], 0, v[194:195]
	s_waitcnt lgkmcnt(1)
	v_pk_mul_f32 v[208:209], v[60:61], v[198:199] op_sel_hi:[1,0]
	v_pk_mul_f32 v[210:211], v[62:63], v[198:199] op_sel_hi:[1,0]
	v_pk_mul_f32 v[110:111], v[110:111], v[196:197] op_sel_hi:[1,0]
	v_pk_mul_f32 v[108:109], v[108:109], v[196:197] op_sel_hi:[1,0]
	v_pk_mul_f32 v[212:213], v[106:107], v[196:197] op_sel_hi:[1,0]
	v_pk_mul_f32 v[196:197], v[104:105], v[196:197] op_sel_hi:[1,0]
	v_pk_mul_f32 v[140:141], v[140:141], v[204:205] op_sel_hi:[1,0]
	v_pk_mul_f32 v[144:145], v[144:145], v[204:205] op_sel_hi:[1,0]
	v_pk_mul_f32 v[142:143], v[142:143], v[204:205] op_sel_hi:[1,0]
	v_pk_mul_f32 v[146:147], v[146:147], v[204:205] op_sel_hi:[1,0]
	v_pk_mul_f32 v[204:205], v[136:137], v[206:207] op_sel_hi:[1,0]
	v_pk_mul_f32 v[214:215], v[138:139], v[206:207] op_sel_hi:[1,0]
	v_pk_mul_f32 v[148:149], v[148:149], v[206:207] op_sel_hi:[1,0]
	v_pk_mul_f32 v[150:151], v[150:151], v[206:207] op_sel_hi:[1,0]
	v_lshl_add_u64 v[174:175], v[174:175], 0, v[64:65]
	v_lshl_add_u64 v[182:183], v[182:183], 0, v[64:65]
	v_lshl_add_u64 v[202:203], v[202:203], 0, v[64:65]
	v_pk_mul_f32 v[56:57], v[56:57], v[198:199] op_sel_hi:[1,0]
	v_pk_mul_f32 v[58:59], v[58:59], v[198:199] op_sel_hi:[1,0]
	v_pk_mul_f32 v[10:11], v[10:11], v[84:85] op_sel_hi:[1,0]
	v_pk_mul_f32 v[14:15], v[14:15], v[84:85] op_sel_hi:[1,0]
	s_and_b64 vcc, exec, s[6:7]
	s_mov_b64 s[6:7], -1
	s_waitcnt vmcnt(1)
	v_pk_mul_f32 v[62:63], v[6:7], v[126:127]
	v_pk_mul_f32 v[60:61], v[4:5], v[124:125]
	s_waitcnt vmcnt(0)
	v_pk_mul_f32 v[106:107], v[2:3], v[122:123]
	v_pk_mul_f32 v[104:105], v[0:1], v[120:121]
	v_pk_mul_f32 v[110:111], v[6:7], v[110:111]
	v_pk_mul_f32 v[108:109], v[4:5], v[108:109]
	v_pk_mul_f32 v[122:123], v[2:3], v[212:213]
	v_pk_mul_f32 v[120:121], v[0:1], v[196:197]
	v_pk_mul_f32 v[126:127], v[6:7], v[140:141]
	v_pk_mul_f32 v[124:125], v[4:5], v[144:145]
	v_pk_mul_f32 v[138:139], v[2:3], v[142:143]
	v_pk_mul_f32 v[136:137], v[0:1], v[146:147]
	v_pk_mul_f32 v[142:143], v[6:7], v[204:205]
	v_pk_mul_f32 v[140:141], v[4:5], v[214:215]
	v_pk_mul_f32 v[146:147], v[2:3], v[148:149]
	v_pk_mul_f32 v[144:145], v[0:1], v[150:151]
	v_pk_mul_f32 v[150:151], v[6:7], v[210:211]
	v_pk_mul_f32 v[148:149], v[4:5], v[208:209]
	global_store_dwordx4 v[170:171], v[60:63], off
	global_store_dwordx4 v[170:171], v[104:107], off offset:16
	global_store_dwordx4 v[172:173], v[108:111], off
	global_store_dwordx4 v[172:173], v[120:123], off offset:16
	global_store_dwordx4 v[174:175], v[124:127], off
	global_store_dwordx4 v[174:175], v[136:139], off offset:16
	global_store_dwordx4 v[182:183], v[140:143], off
	global_store_dwordx4 v[182:183], v[144:147], off offset:16
	global_store_dwordx4 v[202:203], v[148:151], off
	ds_read2_b32 v[104:105], v199 offset0:48 offset1:144
	ds_read2_b32 v[108:109], v199 offset0:144 offset1:160
	v_pk_mul_f32 v[58:59], v[2:3], v[58:59]
	v_pk_mul_f32 v[56:57], v[0:1], v[56:57]
	global_store_dwordx4 v[202:203], v[56:59], off offset:16
	v_lshlrev_b64 v[106:107], 13, v[180:181]
	s_waitcnt lgkmcnt(0)
	v_mov_b32_e32 v110, v109
	v_mov_b32_e32 v56, v105
	v_lshl_add_u64 v[58:59], s[14:15], 0, v[106:107]
	v_pk_mul_f32 v[42:43], v[42:43], v[56:57] op_sel_hi:[1,0]
	v_pk_mul_f32 v[40:41], v[40:41], v[56:57] op_sel_hi:[1,0]
	v_lshl_add_u64 v[58:59], v[58:59], 0, v[64:65]
	v_pk_mul_f32 v[42:43], v[2:3], v[42:43]
	v_pk_mul_f32 v[40:41], v[0:1], v[40:41]
	v_lshlrev_b64 v[120:121], 13, v[178:179]
	global_store_dwordx4 v[58:59], v[40:43], off offset:16
	v_pk_mul_f32 v[26:27], v[26:27], v[110:111] op_sel_hi:[1,0]
	v_pk_mul_f32 v[24:25], v[24:25], v[110:111] op_sel_hi:[1,0]
	v_lshl_add_u64 v[40:41], s[14:15], 0, v[120:121]
	v_lshl_add_u64 v[40:41], v[40:41], 0, v[64:65]
	v_pk_mul_f32 v[26:27], v[2:3], v[26:27]
	v_pk_mul_f32 v[24:25], v[0:1], v[24:25]
	v_pk_mul_f32 v[46:47], v[46:47], v[56:57] op_sel_hi:[1,0]
	v_pk_mul_f32 v[30:31], v[30:31], v[110:111] op_sel_hi:[1,0]
	global_store_dwordx4 v[40:41], v[24:27], off offset:16
	v_pk_mul_f32 v[44:45], v[44:45], v[56:57] op_sel_hi:[1,0]
	v_pk_mul_f32 v[46:47], v[6:7], v[46:47]
	v_pk_mul_f32 v[24:25], v[68:69], v[84:85] op_sel_hi:[1,0]
	v_lshlrev_b64 v[68:69], 13, v[176:177]
	v_pk_mul_f32 v[28:29], v[28:29], v[110:111] op_sel_hi:[1,0]
	v_pk_mul_f32 v[30:31], v[6:7], v[30:31]
	v_pk_mul_f32 v[26:27], v[72:73], v[84:85] op_sel_hi:[1,0]
	v_pk_mul_f32 v[6:7], v[6:7], v[24:25]
	v_lshl_add_u64 v[24:25], s[14:15], 0, v[68:69]
	v_pk_mul_f32 v[44:45], v[4:5], v[44:45]
	v_pk_mul_f32 v[28:29], v[4:5], v[28:29]
	v_pk_mul_f32 v[4:5], v[4:5], v[26:27]
	v_lshl_add_u64 v[24:25], v[24:25], 0, v[64:65]
	global_store_dwordx4 v[58:59], v[44:47], off
	global_store_dwordx4 v[40:41], v[28:31], off
	global_store_dwordx4 v[24:25], v[4:7], off
	v_lshl_add_u64 v[64:65], s[14:15], 0, v[64:65]
	v_pk_mul_f32 v[28:29], v[116:117], v[168:169] op_sel_hi:[1,0]
	v_pk_mul_f32 v[4:5], v[70:71], v[84:85] op_sel_hi:[1,0]
	v_pk_mul_f32 v[6:7], v[74:75], v[84:85] op_sel_hi:[1,0]
	v_pk_mul_f32 v[2:3], v[2:3], v[4:5]
	v_pk_mul_f32 v[0:1], v[0:1], v[6:7]
	global_store_dwordx4 v[24:25], v[0:3], off offset:16
	global_load_dwordx4 v[0:3], v[66:67], off offset:512
	s_nop 0
	global_load_dwordx4 v[4:7], v[66:67], off offset:528
	v_pk_mul_f32 v[24:25], v[118:119], v[168:169] op_sel_hi:[1,0]
	v_pk_mul_f32 v[40:41], v[112:113], v[168:169] op_sel_hi:[1,0]
	v_lshl_add_u64 v[66:67], v[64:65], 0, v[76:77]
	v_pk_mul_f32 v[30:31], v[114:115], v[168:169] op_sel_hi:[1,0]
	v_pk_mul_f32 v[42:43], v[102:103], v[166:167] op_sel_hi:[1,0]
	v_pk_mul_f32 v[44:45], v[100:101], v[166:167] op_sel_hi:[1,0]
	v_pk_mul_f32 v[46:47], v[98:99], v[166:167] op_sel_hi:[1,0]
	v_pk_mul_f32 v[56:57], v[96:97], v[166:167] op_sel_hi:[1,0]
	v_pk_mul_f32 v[58:59], v[88:89], v[86:87] op_sel_hi:[1,0]
	v_pk_mul_f32 v[60:61], v[90:91], v[86:87] op_sel_hi:[1,0]
	v_pk_mul_f32 v[62:63], v[92:93], v[86:87] op_sel_hi:[1,0]
	v_pk_mul_f32 v[74:75], v[94:95], v[86:87] op_sel_hi:[1,0]
	v_lshl_add_u64 v[70:71], v[64:65], 0, v[78:79]
	v_lshl_add_u64 v[72:73], v[64:65], 0, v[82:83]
	v_pk_mul_f32 v[22:23], v[22:23], v[110:111] op_sel_hi:[1,0]
	v_pk_mul_f32 v[20:21], v[20:21], v[110:111] op_sel_hi:[1,0]
	v_pk_mul_f32 v[18:19], v[18:19], v[110:111] op_sel_hi:[1,0]
	v_pk_mul_f32 v[16:17], v[16:17], v[110:111] op_sel_hi:[1,0]
	s_waitcnt vmcnt(1)
	v_pk_mul_f32 v[26:27], v[2:3], v[24:25]
	v_pk_mul_f32 v[24:25], v[0:1], v[28:29]
	s_waitcnt vmcnt(0)
	v_pk_mul_f32 v[28:29], v[4:5], v[40:41]
	v_pk_mul_f32 v[30:31], v[6:7], v[30:31]
	v_pk_mul_f32 v[42:43], v[2:3], v[42:43]
	v_pk_mul_f32 v[40:41], v[0:1], v[44:45]
	v_pk_mul_f32 v[46:47], v[6:7], v[46:47]
	v_pk_mul_f32 v[44:45], v[4:5], v[56:57]
	v_pk_mul_f32 v[58:59], v[2:3], v[58:59]
	v_pk_mul_f32 v[56:57], v[0:1], v[60:61]
	v_pk_mul_f32 v[62:63], v[6:7], v[62:63]
	v_pk_mul_f32 v[60:61], v[4:5], v[74:75]
	global_store_dwordx4 v[66:67], v[24:27], off offset:512
	global_store_dwordx4 v[66:67], v[28:31], off offset:528
	global_store_dwordx4 v[70:71], v[40:43], off offset:512
	global_store_dwordx4 v[70:71], v[44:47], off offset:528
	global_store_dwordx4 v[72:73], v[56:59], off offset:512
	global_store_dwordx4 v[72:73], v[60:63], off offset:528
	v_pk_mul_f32 v[24:25], v[128:129], v[104:105] op_sel_hi:[1,0]
	v_pk_mul_f32 v[28:29], v[132:133], v[104:105] op_sel_hi:[1,0]
	v_pk_mul_f32 v[26:27], v[2:3], v[24:25]
	v_pk_mul_f32 v[24:25], v[0:1], v[28:29]
	v_lshl_add_u64 v[28:29], v[64:65], 0, v[80:81]
	global_store_dwordx4 v[28:29], v[24:27], off offset:512
	v_pk_mul_f32 v[30:31], v[134:135], v[104:105] op_sel_hi:[1,0]
	v_pk_mul_f32 v[22:23], v[2:3], v[22:23]
	v_pk_mul_f32 v[24:25], v[130:131], v[104:105] op_sel_hi:[1,0]
	v_pk_mul_f32 v[20:21], v[0:1], v[20:21]
	v_pk_mul_f32 v[26:27], v[6:7], v[24:25]
	v_pk_mul_f32 v[24:25], v[4:5], v[30:31]
	global_store_dwordx4 v[28:29], v[24:27], off offset:528
	v_lshl_add_u64 v[28:29], v[64:65], 0, v[194:195]
	v_pk_mul_f32 v[30:31], v[32:33], v[108:109] op_sel_hi:[1,0]
	v_pk_mul_f32 v[24:25], v[52:53], v[200:201] op_sel_hi:[1,0]
	v_pk_mul_f32 v[26:27], v[54:55], v[200:201] op_sel_hi:[1,0]
	v_pk_mul_f32 v[24:25], v[0:1], v[24:25]
	v_pk_mul_f32 v[26:27], v[2:3], v[26:27]
	global_store_dwordx4 v[28:29], v[24:27], off offset:512
	v_pk_mul_f32 v[18:19], v[6:7], v[18:19]
	v_pk_mul_f32 v[16:17], v[4:5], v[16:17]
	v_pk_mul_f32 v[24:25], v[48:49], v[200:201] op_sel_hi:[1,0]
	v_pk_mul_f32 v[26:27], v[50:51], v[200:201] op_sel_hi:[1,0]
	v_pk_mul_f32 v[24:25], v[4:5], v[24:25]
	v_pk_mul_f32 v[26:27], v[6:7], v[26:27]
	global_store_dwordx4 v[28:29], v[24:27], off offset:528
	v_pk_mul_f32 v[28:29], v[36:37], v[108:109] op_sel_hi:[1,0]
	s_nop 0
	v_pk_mul_f32 v[24:25], v[38:39], v[108:109] op_sel_hi:[1,0]
	s_nop 0
	v_pk_mul_f32 v[26:27], v[2:3], v[24:25]
	v_pk_mul_f32 v[24:25], v[0:1], v[28:29]
	v_lshl_add_u64 v[28:29], v[64:65], 0, v[106:107]
	global_store_dwordx4 v[28:29], v[24:27], off offset:512
	v_pk_mul_f32 v[2:3], v[2:3], v[10:11]
	v_pk_mul_f32 v[0:1], v[0:1], v[14:15]
	v_pk_mul_f32 v[24:25], v[34:35], v[108:109] op_sel_hi:[1,0]
	v_lshl_add_u64 v[10:11], v[64:65], 0, v[68:69]
	v_pk_mul_f32 v[26:27], v[6:7], v[24:25]
	v_pk_mul_f32 v[24:25], v[4:5], v[30:31]
	global_store_dwordx4 v[28:29], v[24:27], off offset:528
	s_nop 1
	v_lshl_add_u64 v[24:25], v[64:65], 0, v[120:121]
	global_store_dwordx4 v[24:25], v[20:23], off offset:512
	global_store_dwordx4 v[10:11], v[0:3], off offset:512
	global_store_dwordx4 v[24:25], v[16:19], off offset:528
	s_nop 0
	v_pk_mul_f32 v[0:1], v[8:9], v[84:85] op_sel_hi:[1,0]
	v_pk_mul_f32 v[8:9], v[12:13], v[84:85] op_sel_hi:[1,0]
	v_pk_mul_f32 v[2:3], v[6:7], v[0:1]
	v_pk_mul_f32 v[0:1], v[4:5], v[8:9]
	global_store_dwordx4 v[10:11], v[0:3], off offset:528
	s_waitcnt lgkmcnt(0)
	s_barrier
	s_cbranch_vccnz .LBB0_872
	s_andn2_b64 vcc, exec, s[18:19]
	s_cbranch_vccnz .LBB0_871
	s_barrier
	s_branch .LBB0_871
